# differential attention loop: last tile pair peeled, steady-state pairs without has-next / skip / mask checks
# speedup vs baseline: 1.0074x; 1.0025x over previous
; template <bool DIFF>
; __device__ __forceinline__ void attn_unit(CA& A, int l, int b, int hh, int qb, LAS unsigned char* lds, float lam, float lam_init) {
;     ...
;     const int tid = otid(), lane = tid & 63, wid = __builtin_amdgcn_readfirstlane(tid >> 6), r32 = lane & 31, hi = lane >> 5;
;     const int q0 = qb * QROWS, wq = DIFF ? (wid & 3) * 32 : wid * 32, strm = DIFF ? (wid >> 2) : 0;
;     const bf16_t* Zb = (const bf16_t*)(A.ws + WS_Z) + (size_t)b * SEQ * ZC;
;     bf16_t* MIX = (bf16_t*)(A.ws + WS_MIX);
;     const int qcol = DIFF ? (DIFF_Q0 + hh * 64 + strm * 32) : (FOX_Q0 + hh * 64);
;     const int kcol = DIFF ? (DIFF_K0 + hh * 64) : (FOX_K0 + hh * 64);
;     const int vcol = DIFF ? (DIFF_V0 + hh * 64) : (FOX_V0 + hh * 64);
;     const float* gq = DIFF ? A.diff_qk_g + l * 64 : A.fox_qk_g + l * 128;
;     const float* gk = gq + DQK;
;     const int skey = tid >> 3, sch = tid & 7;
;     const bf16_t* kp = Zb + (size_t)skey * ZC + kcol + 8 * sch;
;     const bf16_t* vp = Zb + (size_t)lane * ZC + vcol + 8 * wid;
;     const float* ncp = (const float*)(A.ws + WS_NEGC) + (size_t)(b * 4 + hh) * SEQ;
;     const int NT = (q0 + QROWS) / 64;
;     v4u kraw, vraw; float ncv = 0.f;
;     v4u qraw[NS];
;     {
;         const bf16_t* qp = Zb + (size_t)(q0 + wq + r32) * ZC + qcol + 8 * hi;
; #pragma unroll
;         for (int s = 0; s < NS; ++s) qraw[s] = *(const v4u*)(qp + 16 * s);
;     }
;     { const int t0_ = DIFF ? 0 : NT - 1; kraw = *(const v4u*)(kp + (size_t)t0_ * 64 * ZC); vraw = *(const v4u*)(vp + (size_t)t0_ * 64 * ZC); }
;     const float gkl = gk[lane & (DQK - 1)];
;     bf16x8 qf[NS]; float qn2 = 0.f;
; #pragma unroll
;     for (int s = 0; s < NS; ++s) { qf[s] = __builtin_bit_cast(bf16x8, qraw[s]);
; #pragma unroll
;         for (int i = 0; i < 4; ++i) qn2 += bflo(qraw[s][i]) * bflo(qraw[s][i]) + bfhi(qraw[s][i]) * bfhi(qraw[s][i]); }
;     qn2 += shx(qn2, 32);
;     float qkb;
;     {
;         float gm = fabsf(gkl);
; #pragma unroll
;         for (int o_ = 1; o_ < 64; o_ <<= 1) gm = fmaxf(gm, shx(gm, o_));
;         qkb = sqrtf(qn2) * sqrtf((float)DQK) * gm * 1.02f;
; __device__ __forceinline__ void mix_phase(CA& A0, int l, LAS unsigned char* lds) {
;     ...
;         if (it < 256) ait = it; else if (it >= 256 + MIX_GMLP_ITEMS + MIX_CONV_ITEMS) ait = it - MIX_GMLP_ITEMS - MIX_CONV_ITEMS;
;         if (ait >= 0) {
.LBB0_738:
	s_andn2_b64 vcc, exec, s[4:5]
	s_cbranch_vccnz .LBB0_658
	s_and_b32 s4, s20, 0xffff
	s_mul_i32 s4, s4, 0xaaab
	s_lshr_b32 s12, s4, 21
	s_mul_i32 s4, s12, 48
	s_sub_i32 s4, s20, s4
	s_sub_i32 s14, 15, s12
	s_and_b32 s13, s4, 0xffff
	s_cmp_gt_u32 s13, 15
	s_mov_b64 s[4:5], -1
	s_cbranch_scc0 .LBB0_756
	v_mov_b32_e32 v1, v179
	s_load_dwordx2 s[6:7], s[34:35], 0xc8
	s_load_dwordx2 s[10:11], s[34:35], 0x58
	v_readfirstlane_b32 s17, v1
	s_bfe_u32 s16, s13, 0x20002
	s_and_b32 s4, s13, 48
	s_ashr_i32 s27, s17, 6
	s_lshl_b32 s5, s14, 8
	s_cmp_eq_u32 s4, 16
	s_cselect_b32 s29, 0x80, 0
	s_lshl_b32 s18, s27, 5
	s_or_b32 s19, s29, s5
	s_and_b32 s20, s18, 0x60
	s_ashr_i32 s24, s17, 8
	s_mul_i32 s30, s16, 0x1400000
	s_waitcnt lgkmcnt(0)
	s_add_u32 s4, s6, s30
	s_addc_u32 s5, s7, 0
	s_add_u32 s4, s4, 0x9500000
	s_addc_u32 s5, s5, 0
	s_lshl_b32 s8, s13, 6
	s_and_b32 s15, s8, 0xc0
	s_lshl_b32 s8, s88, 6
	s_lshl_b32 s37, s24, 5
	s_ashr_i32 s9, s8, 31
	s_add_i32 s38, s37, s15
	s_lshl_b64 s[8:9], s[8:9], 2
	v_and_b32_e32 v137, 31, v1
	s_add_u32 s10, s10, s8
	s_addc_u32 s11, s11, s9
	v_lshlrev_b32_e32 v4, 2, v137
	global_load_dword v10, v4, s[10:11] offset:128
	s_or_b32 s25, s20, s19
	v_or_b32_e32 v138, s25, v137
	v_mul_i32_i24_e32 v2, 0xa00, v138
	v_mov_b32_e32 v3, v0
	v_bfe_u32 v14, v1, 5, 1
	v_lshl_add_u64 v[2:3], v[2:3], 1, s[4:5]
	s_ashr_i32 s39, s38, 31
	v_lshl_add_u64 v[2:3], s[38:39], 1, v[2:3]
	v_lshlrev_b32_e32 v130, 4, v14
	v_mov_b32_e32 v131, v0
	v_lshl_add_u64 v[2:3], v[2:3], 0, v[130:131]
	global_load_dwordx4 v[112:115], v[2:3], off
	global_load_dwordx4 v[116:119], v[2:3], off offset:32
	v_and_b32_e32 v16, 63, v1
	v_mul_u32_u24_e32 v4, 0xa00, v16
	v_mov_b32_e32 v5, v0
	v_ashrrev_i32_e32 v17, 3, v1
	v_lshlrev_b32_e32 v4, 1, v4
	v_mov_b64_e32 v[6:7], s[4:5]
	v_lshl_add_u64 v[8:9], s[4:5], 0, v[4:5]
	v_mad_i64_i32 v[6:7], s[4:5], v17, s93, v[6:7]
	v_readlane_b32 s38, v237, 58
	v_lshlrev_b32_e32 v1, 4, v1
	v_readlane_b32 s39, v237, 59
	s_lshl_b32 s38, s15, 1
	s_lshl_b32 s4, s27, 3
	v_mov_b32_e32 v3, v0
	v_and_b32_e32 v2, 0x70, v1
	v_lshl_add_u64 v[6:7], v[6:7], 0, s[38:39]
	s_ashr_i32 s5, s4, 31
	v_lshl_add_u64 v[8:9], v[8:9], 0, s[38:39]
	v_lshl_add_u64 v[6:7], v[6:7], 0, v[2:3]
	s_lshl_b64 s[10:11], s[4:5], 1
	v_lshl_add_u64 v[8:9], v[8:9], 0, s[10:11]
	global_load_dwordx4 v[120:123], v[6:7], off offset:512
	global_load_dwordx4 v[124:127], v[8:9], off offset:1024
	v_mov_b32_e32 v15, v179
	v_mov_b32_e32 v11, v179
	v_mov_b32_e32 v12, v179
	v_lshlrev_b32_e32 v1, 2, v11
	v_bitop3_b32 v1, v1, 4, v220 bitop3:0x6c
	s_mov_b32 s4, 0xf800000
	v_lshlrev_b32_e32 v3, 2, v12
	v_bitop3_b32 v3, v3, 8, v220 bitop3:0x6c
	s_mulk_i32 s27, 0x440
	s_add_i32 s28, s19, 0x80
	v_lshlrev_b32_e32 v131, 2, v14
	s_mov_b32 s26, 63
	s_mov_b32 s31, 0
	v_mul_u32_u24_e32 v142, 0x90, v137
	v_mul_u32_u24_e32 v145, 0x88, v137
	s_waitcnt vmcnt(4)
	v_and_b32_e32 v6, 0x7fffffff, v10
	ds_bpermute_b32 v1, v1, v6
	v_max_f32_e64 v12, |v10|, |v10|
	s_waitcnt lgkmcnt(0)
	v_max_f32_e32 v1, v1, v1
	v_max_f32_e32 v1, v12, v1
	ds_bpermute_b32 v3, v3, v1
	s_waitcnt vmcnt(3)
	v_and_b32_e32 v19, 0xffff0000, v112
	v_and_b32_e32 v21, 0xffff0000, v113
	s_waitcnt lgkmcnt(0)
	v_max_f32_e32 v3, v3, v3
	v_max_f32_e32 v1, v1, v3
	v_mov_b32_e32 v3, v179
	v_lshlrev_b32_e32 v18, 16, v112
	v_lshlrev_b32_e32 v3, 2, v3
	v_bitop3_b32 v3, v3, 16, v220 bitop3:0x6c
	ds_bpermute_b32 v3, v3, v1
	v_lshlrev_b32_e32 v20, 16, v113
	v_and_b32_e32 v9, 0xffff0000, v115
	v_and_b32_e32 v8, 0xffff0000, v114
	v_mul_f32_e32 v19, v19, v19
	s_waitcnt lgkmcnt(0)
	v_max_f32_e32 v3, v3, v3
	v_max_f32_e32 v1, v1, v3
	v_mov_b32_e32 v3, v179
	v_mul_f32_e32 v21, v21, v21
	v_lshlrev_b32_e32 v3, 2, v3
	v_bitop3_b32 v3, v3, 32, v220 bitop3:0x6c
	ds_bpermute_b32 v3, v3, v1
	v_lshlrev_b32_e32 v7, 16, v115
	v_lshlrev_b32_e32 v6, 16, v114
	v_pk_mul_f32 v[8:9], v[8:9], v[8:9]
	v_fmac_f32_e32 v19, v18, v18
	v_fmac_f32_e32 v21, v20, v20
	v_pk_fma_f32 v[6:7], v[6:7], v[6:7], v[8:9]
	v_add_f32_e32 v8, v19, v21
	s_waitcnt vmcnt(2)
	v_and_b32_e32 v13, 0xffff0000, v117
	v_add_f32_e32 v6, v6, v8
	v_and_b32_e32 v12, 0xffff0000, v116
	s_waitcnt lgkmcnt(0)
	v_max_f32_e32 v3, v3, v3
	v_lshlrev_b32_e32 v11, 16, v117
	v_lshlrev_b32_e32 v10, 16, v116
	v_add_f32_e32 v8, v7, v6
	v_pk_mul_f32 v[6:7], v[12:13], v[12:13]
	v_max_f32_e32 v1, v1, v3
	v_mov_b32_e32 v3, v179
	v_pk_fma_f32 v[6:7], v[10:11], v[10:11], v[6:7]
	v_and_b32_e32 v9, 0xffff0000, v119
	v_add_f32_e32 v6, v6, v8
	v_and_b32_e32 v8, 0xffff0000, v118
	v_lshlrev_b32_e32 v3, 2, v3
	v_add_f32_e32 v10, v7, v6
	v_lshlrev_b32_e32 v7, 16, v119
	v_lshlrev_b32_e32 v6, 16, v118
	v_pk_mul_f32 v[8:9], v[8:9], v[8:9]
	v_bitop3_b32 v3, v3, 64, v220 bitop3:0x6c
	v_pk_fma_f32 v[6:7], v[6:7], v[6:7], v[8:9]
	ds_bpermute_b32 v3, v3, v1
	v_add_f32_e32 v6, v6, v10
	v_add_f32_e32 v6, v7, v6
	v_lshlrev_b32_e32 v7, 2, v15
	v_bitop3_b32 v7, v7, s33, v220 bitop3:0x6c
	ds_bpermute_b32 v7, v7, v6
	s_waitcnt lgkmcnt(1)
	v_max_f32_e32 v3, v3, v3
	v_max_f32_e32 v1, v1, v3
	v_mov_b32_e32 v3, v179
	s_waitcnt lgkmcnt(0)
	v_add_f32_e32 v6, v6, v7
	v_lshlrev_b32_e32 v3, 2, v3
	v_bitop3_b32 v3, v3, s33, v220 bitop3:0x6c
	ds_bpermute_b32 v3, v3, v1
	v_mul_f32_e32 v7, 0x4f800000, v6
	v_cmp_gt_f32_e32 vcc, s4, v6
	v_lshlrev_b32_e32 v8, 3, v14
	v_mov_b32_e32 v14, v0
	v_cndmask_b32_e32 v6, v6, v7, vcc
	v_sqrt_f32_e32 v7, v6
	s_waitcnt lgkmcnt(0)
; #define LAS __attribute__((address_space(3)))
; template <bool DIFF>
; __device__ __forceinline__ void attn_unit(CA& A, int l, int b, int hh, int qb, LAS unsigned char* lds, float lam, float lam_init) {
;     ...
;     {
;         float gm = fabsf(gkl);
; #pragma unroll
;         for (int o_ = 1; o_ < 64; o_ <<= 1) gm = fmaxf(gm, shx(gm, o_));
;         qkb = sqrtf(qn2) * sqrtf((float)DQK) * gm * 1.02f;
;     }
;     ...
;     if (!DIFF) {
;         if (tid == 0) { const unsigned* fl = (const unsigned*)(A.ws + WS_CTL) + 128 + l * 16 + b * 4 + hh; unsigned spins = 0;
;             while (__hip_atomic_load(fl, __ATOMIC_RELAXED, __HIP_MEMORY_SCOPE_AGENT) == 0u) { __builtin_amdgcn_s_sleep(2); if (++spins > (1u << 22)) break; } }
;         __syncthreads();
;     }
;     float ncq = 0.f;
;     if (!DIFF) { if (tid < 64) ncv = ncp[(NT - 1) * 64 + tid]; ncq = ncp[q0 + wq + r32]; }
;     ATT_WRITE(0);
;     __syncthreads();
;     f32x16 o[2], ol; float m_ref = 0.f;
; #pragma unroll
;     for (int r = 0; r < 16; ++r) { o[0][r] = 0.f; o[1][r] = 0.f; ol[r] = 0.f; }
;     f32x16 negm;
; #pragma unroll
;     for (int r = 0; r < 16; ++r) negm[r] = 0.f;
;     const bf16x8 ones = {0x3F80, 0x3F80, 0x3F80, 0x3F80, 0x3F80, 0x3F80, 0x3F80, 0x3F80};
;     const int qfirst = q0 + wq, qlast = qfirst + 31, qmine = qfirst + r32;
;     const int koff = DIFF ? strm * 32 : 0;
;     if (DIFF) {
;         m_ref = qkb;
; #pragma unroll
;         for (int r = 0; r < 16; ++r) negm[r] = -qkb;
;     } else {
;         m_ref = qkb + ncq;
;     }
;     volatile LAS int* votes = (volatile LAS int*)(lds + LDS_MAIN + 64);
;     ...
;         if (has_next) { ATT_LOAD(DIFF ? t + 1 : t - 1); if (!DIFF) nc_hi = ncp[key0 - 1]; }
;         if (key0 <= qlast) {
;             const LAS unsigned char* Kb = lds + AL_KS + buf * AL_KSZ;
;             const LAS unsigned char* Vb = lds + AL_VT + buf * AL_VSZ;
;             f32x16 p[2];
; #pragma unroll
;             for (int kt = 0; kt < 2; ++kt) {
;                 if (!DIFF) {
;                     const LAS float* nc = (const LAS float*)(lds + AL_NC + buf * 512) + 32 * kt + 4 * hi;
; #pragma unroll
;                     for (int g = 0; g < 4; ++g) { const f32x4 c4 = *(const LAS f32x4*)(nc + 8 * g); p[kt][4 * g] = c4[0]; p[kt][4 * g + 1] = c4[1]; p[kt][4 * g + 2] = c4[2]; p[kt][4 * g + 3] = c4[3]; }
;                 }
; #pragma unroll
;                 for (int s = 0; s < NS; ++s) {
	v_max_f32_e32 v3, v3, v3
	v_max_f32_e32 v1, v1, v3
	v_mov_b32_e32 v15, v0
	v_add_u32_e32 v3, -1, v7
	v_fma_f32 v9, -v3, v7, v6
	v_cmp_ge_f32_e64 s[4:5], 0, v9
	v_add_u32_e32 v9, 1, v7
	v_add_u32_e32 v141, 0, v8
	v_cndmask_b32_e64 v3, v7, v3, s[4:5]
	v_fma_f32 v7, -v9, v7, v6
	v_cmp_lt_f32_e64 s[4:5], 0, v7
	v_mov_b32_e32 v10, v0
	v_mov_b32_e32 v11, v0
	v_cndmask_b32_e64 v3, v3, v9, s[4:5]
	s_add_i32 s4, s27, 0
	v_lshl_add_u32 v140, v16, 1, s4
	s_and_b32 s4, s13, 3
	s_lshl_b32 s4, s4, 7
	v_mul_f32_e32 v7, 0x37800000, v3
	s_lshr_b32 s27, s28, 6
	s_or_b32 s28, s25, 31
	s_or_b32 s38, s30, s4
	v_cndmask_b32_e32 v3, v3, v7, vcc
	v_cmp_class_f32_e32 vcc, v6, v219
	s_movk_i32 s5, 0x90
	s_add_u32 s4, s38, s10
	v_cndmask_b32_e32 v3, v3, v6, vcc
	v_mul_lo_u32 v6, v17, s5
	v_mad_u32_u24 v144, v137, s5, v224
	s_addc_u32 s5, 0, s11
	s_add_u32 s4, s6, s4
	s_addc_u32 s5, s7, s5
	v_lshl_add_u64 v[4:5], s[4:5], 0, v[4:5]
	s_mov_b64 s[4:5], 0x9550400
	v_lshl_add_u64 v[132:133], v[4:5], 0, s[4:5]
	s_mov_b32 s5, s39
	v_writelane_b32 v237, s4, 58
	v_mov_b64_e32 v[4:5], s[38:39]
	v_mul_f32_e32 v3, 0x40b504f3, v3
	v_writelane_b32 v237, s5, 59
	v_mad_i64_i32 v[4:5], s[4:5], v17, s93, v[4:5]
	v_or_b32_e32 v4, v4, v2
	v_add3_u32 v139, 0, v6, v2
	v_mul_f32_e32 v1, v3, v1
	v_lshl_add_u64 v[2:3], s[6:7], 0, v[4:5]
	s_mov_b64 s[4:5], 0x9550200
	v_lshl_add_u64 v[134:135], v[2:3], 0, s[4:5]
	s_lshl_b32 s4, s12, 8
	v_mul_f32_e32 v48, 0xbf828f5c, v1
	v_or_b32_e32 v1, s37, v8
	s_sub_i32 s4, s29, s4
	v_lshlrev_b32_e32 v143, 1, v1
	s_addk_i32 s4, 0xf80
	v_mov_b32_e32 v1, v0
	v_mov_b32_e32 v2, v0
	v_mov_b32_e32 v3, v0
	v_mov_b32_e32 v4, v0
	v_mov_b32_e32 v5, v0
	v_mov_b32_e32 v6, v0
	v_mov_b32_e32 v7, v0
	v_mov_b32_e32 v8, v0
	v_mov_b32_e32 v9, v0
	v_mov_b32_e32 v12, v0
	v_mov_b32_e32 v13, v0
	v_mov_b64_e32 v[46:47], v[14:15]
	v_mov_b64_e32 v[30:31], v[14:15]
	v_mov_b64_e32 v[78:79], v[14:15]
	v_mov_b32_e32 v49, v48
	v_mov_b32_e32 v50, v48
	v_mov_b32_e32 v51, v48
	v_mov_b32_e32 v52, v48
	v_mov_b32_e32 v53, v48
	v_mov_b32_e32 v54, v48
	v_mov_b32_e32 v55, v48
	v_mov_b32_e32 v56, v48
	v_mov_b32_e32 v57, v48
	v_mov_b32_e32 v58, v48
	v_mov_b32_e32 v59, v48
	v_mov_b32_e32 v60, v48
	v_mov_b32_e32 v61, v48
	v_mov_b32_e32 v62, v48
	v_mov_b32_e32 v63, v48
	s_lshr_b32 s10, s4, 6
	v_mov_b64_e32 v[44:45], v[12:13]
	v_mov_b64_e32 v[42:43], v[10:11]
	v_mov_b64_e32 v[40:41], v[8:9]
	v_mov_b64_e32 v[38:39], v[6:7]
	v_mov_b64_e32 v[36:37], v[4:5]
	v_mov_b64_e32 v[34:35], v[2:3]
	v_mov_b64_e32 v[32:33], v[0:1]
	v_mov_b64_e32 v[28:29], v[12:13]
	v_mov_b64_e32 v[26:27], v[10:11]
	v_mov_b64_e32 v[24:25], v[8:9]
	v_mov_b64_e32 v[22:23], v[6:7]
	v_mov_b64_e32 v[20:21], v[4:5]
	v_mov_b64_e32 v[18:19], v[2:3]
	v_mov_b64_e32 v[16:17], v[0:1]
	v_mov_b64_e32 v[76:77], v[12:13]
	v_mov_b64_e32 v[74:75], v[10:11]
	v_mov_b64_e32 v[72:73], v[8:9]
	v_mov_b64_e32 v[70:71], v[6:7]
	v_mov_b64_e32 v[68:69], v[4:5]
	v_mov_b64_e32 v[66:67], v[2:3]
	v_mov_b64_e32 v[64:65], v[0:1]
	s_waitcnt vmcnt(1)
	ds_write_b128 v139, v[120:123]
	s_waitcnt vmcnt(0)
	ds_write_b16 v140, v124 offset:18432
	ds_write_b16_d16_hi v140, v124 offset:18568
	ds_write_b16 v140, v125 offset:18704
	ds_write_b16_d16_hi v140, v125 offset:18840
	ds_write_b16 v140, v126 offset:18976
	ds_write_b16_d16_hi v140, v126 offset:19112
	ds_write_b16 v140, v127 offset:19248
	ds_write_b16_d16_hi v140, v127 offset:19384
	s_waitcnt lgkmcnt(0)
	s_barrier
	v_add_u32_e32 v200, v142, v143
	v_add_u32_e32 v201, v144, v143
	v_add_u32_e32 v214, v141, v145
	v_mov_b32_e32 v204, s36
	v_mov_b32_e32 v205, s36
	v_mov_b32_e32 v206, s36
	v_mov_b32_e32 v207, s36
	v_add_u32_e32 v202, 0x4800, v214
	v_add_u32_e32 v203, 0x5800, v214
	v_add_u32_e32 v212, 0x6a00, v214
	v_add_u32_e32 v213, 0x7a00, v214
	s_mov_b64 s[4:5], 0x50000
	s_add_i32 s29, s27, -2
	s_cmp_ge_u32 s31, s29
	s_cbranch_scc1 .Lmy_d_final
.LBB0_741:
	global_load_dwordx4 v[120:123], v[134:135], off
	global_load_dwordx4 v[124:127], v[132:133], off
	ds_read_b128 v[148:151], v200
	ds_read_b128 v[152:155], v201
	ds_read_b128 v[156:159], v200 offset:32
	ds_read_b128 v[160:163], v201 offset:32
	s_waitcnt lgkmcnt(2)
	v_mfma_f32_32x32x16_bf16 v[96:111], v[148:151], v[112:115], v[48:63]
	v_mfma_f32_32x32x16_bf16 v[80:95], v[152:155], v[112:115], v[48:63]
	s_waitcnt lgkmcnt(0)
	v_mfma_f32_32x32x16_bf16 v[96:111], v[156:159], v[116:119], v[96:111]
	v_mfma_f32_32x32x16_bf16 v[80:95], v[160:163], v[116:119], v[80:95]
	ds_read2_b64 v[164:167], v202 offset0:0 offset1:2
	ds_read2_b64 v[168:171], v203 offset0:32 offset1:34
	ds_read2_b64 v[172:175], v202 offset0:4 offset1:6
	ds_read2_b64 v[180:183], v203 offset0:36 offset1:38
	ds_read2_b64 v[184:187], v202 offset0:8 offset1:10
	ds_read2_b64 v[188:191], v203 offset0:40 offset1:42
	ds_read2_b64 v[192:195], v202 offset0:12 offset1:14
	ds_read2_b64 v[196:199], v203 offset0:44 offset1:46
	s_nop 2
	v_exp_f32_e32 v96, v96
	v_exp_f32_e32 v97, v97
	v_exp_f32_e32 v98, v98
	v_exp_f32_e32 v99, v99
	v_exp_f32_e32 v100, v100
	v_exp_f32_e32 v101, v101
	v_exp_f32_e32 v102, v102
	v_exp_f32_e32 v103, v103
	v_cvt_pk_bf16_f32 v6, v96, v97
	v_cvt_pk_bf16_f32 v7, v98, v99
	v_cvt_pk_bf16_f32 v8, v100, v101
	v_cvt_pk_bf16_f32 v9, v102, v103
	v_exp_f32_e32 v104, v104
	v_exp_f32_e32 v105, v105
	s_waitcnt lgkmcnt(6)
	v_mfma_f32_32x32x16_bf16 v[32:47], v[164:167], v[6:9], v[32:47]
	v_exp_f32_e32 v106, v106
	v_exp_f32_e32 v107, v107
	v_cvt_pk_bf16_f32 v208, v104, v105
	v_mfma_f32_32x32x16_bf16 v[16:31], v[168:171], v[6:9], v[16:31]
	v_exp_f32_e32 v108, v108
	v_exp_f32_e32 v109, v109
	v_cvt_pk_bf16_f32 v209, v106, v107
	v_mfma_f32_32x32x16_bf16 v[64:79], v[204:207], v[6:9], v[64:79]
	v_exp_f32_e32 v110, v110
	v_exp_f32_e32 v111, v111
	v_cvt_pk_bf16_f32 v210, v108, v109
	v_exp_f32_e32 v80, v80
	v_cvt_pk_bf16_f32 v211, v110, v111
	v_exp_f32_e32 v81, v81
	s_waitcnt lgkmcnt(4)
; template <bool DIFF>
; __device__ __forceinline__ void attn_unit(CA& A, int l, int b, int hh, int qb, LAS unsigned char* lds, float lam, float lam_init) {
;     ...
;         if (has_next) { ATT_LOAD(DIFF ? t + 1 : t - 1); if (!DIFF) nc_hi = ncp[key0 - 1]; }
;         if (key0 <= qlast) {
;             const LAS unsigned char* Kb = lds + AL_KS + buf * AL_KSZ;
;             const LAS unsigned char* Vb = lds + AL_VT + buf * AL_VSZ;
;             f32x16 p[2];
; #pragma unroll
;             for (int kt = 0; kt < 2; ++kt) {
;                 if (!DIFF) {
;                     const LAS float* nc = (const LAS float*)(lds + AL_NC + buf * 512) + 32 * kt + 4 * hi;
; #pragma unroll
;                     for (int g = 0; g < 4; ++g) { const f32x4 c4 = *(const LAS f32x4*)(nc + 8 * g); p[kt][4 * g] = c4[0]; p[kt][4 * g + 1] = c4[1]; p[kt][4 * g + 2] = c4[2]; p[kt][4 * g + 3] = c4[3]; }
;                 }
; #pragma unroll
;                 for (int s = 0; s < NS; ++s) {
;                     const bf16x8 a = *(const LAS bf16x8*)(Kb + (32 * kt + r32) * 144 + (koff + 16 * s + 8 * hi) * 2);
;                     if (DIFF && s == 0) p[kt] = __builtin_amdgcn_mfma_f32_32x32x16_bf16(a, qf[s], negm, 0, 0, 0);
;                     else p[kt] = __builtin_amdgcn_mfma_f32_32x32x16_bf16(a, qf[s], p[kt], 0, 0, 0);
;                 }
;             }
;             if (!DIFF) {
; #pragma unroll
;                 for (int kt = 0; kt < 2; ++kt)
; #pragma unroll
;                     for (int r = 0; r < 16; ++r) p[kt][r] -= m_ref;
;             }
;             if (key0 + 63 > qfirst) {
; #pragma unroll
;                 for (int kt = 0; kt < 2; ++kt)
; #pragma unroll
;                     for (int r = 0; r < 16; ++r) if (key0 + 32 * kt + crow(r, hi) > qmine) p[kt][r] = -1e30f;
;             }
;             first = false;
; #pragma unroll
;             for (int kt = 0; kt < 2; ++kt)
; #pragma unroll
;                 for (int r = 0; r < 16; ++r) p[kt][r] = __builtin_amdgcn_exp2f(p[kt][r]);
;             bf16x8 pb[2][2];
; #pragma unroll
;             for (int kt = 0; kt < 2; ++kt)
; #pragma unroll
;                 for (int i = 0; i < 2; ++i) { v4u w;
; #pragma unroll
;                     for (int j = 0; j < 4; ++j) w[j] = pk2(p[kt][8 * i + 2 * j], p[kt][8 * i + 2 * j + 1]);
;                     pb[kt][i] = __builtin_bit_cast(bf16x8, w); }
; #pragma unroll
	v_mfma_f32_32x32x16_bf16 v[32:47], v[172:175], v[208:211], v[32:47]
	v_exp_f32_e32 v82, v82
	v_exp_f32_e32 v83, v83
	v_cvt_pk_bf16_f32 v6, v80, v81
	v_mfma_f32_32x32x16_bf16 v[16:31], v[180:183], v[208:211], v[16:31]
	v_exp_f32_e32 v84, v84
	v_exp_f32_e32 v85, v85
	v_cvt_pk_bf16_f32 v7, v82, v83
	v_mfma_f32_32x32x16_bf16 v[64:79], v[204:207], v[208:211], v[64:79]
	v_exp_f32_e32 v86, v86
	v_exp_f32_e32 v87, v87
	v_cvt_pk_bf16_f32 v8, v84, v85
	v_exp_f32_e32 v88, v88
	v_cvt_pk_bf16_f32 v9, v86, v87
	v_exp_f32_e32 v89, v89
	s_waitcnt lgkmcnt(2)
	v_mfma_f32_32x32x16_bf16 v[32:47], v[184:187], v[6:9], v[32:47]
	v_exp_f32_e32 v90, v90
	v_exp_f32_e32 v91, v91
	v_cvt_pk_bf16_f32 v208, v88, v89
	v_mfma_f32_32x32x16_bf16 v[16:31], v[188:191], v[6:9], v[16:31]
	v_exp_f32_e32 v92, v92
	v_exp_f32_e32 v93, v93
	v_cvt_pk_bf16_f32 v209, v90, v91
	v_mfma_f32_32x32x16_bf16 v[64:79], v[204:207], v[6:9], v[64:79]
	v_exp_f32_e32 v94, v94
	v_exp_f32_e32 v95, v95
	v_cvt_pk_bf16_f32 v210, v92, v93
	s_nop 0
	v_cvt_pk_bf16_f32 v211, v94, v95
	s_waitcnt lgkmcnt(0)
	s_nop 0
	v_mfma_f32_32x32x16_bf16 v[32:47], v[192:195], v[208:211], v[32:47]
	v_mfma_f32_32x32x16_bf16 v[16:31], v[196:199], v[208:211], v[16:31]
	v_mfma_f32_32x32x16_bf16 v[64:79], v[204:207], v[208:211], v[64:79]
	s_waitcnt vmcnt(1)
	ds_write_b128 v139, v[120:123] offset:9216
	s_waitcnt vmcnt(0)
	ds_write_b16 v140, v124 offset:27136
	ds_write_b16_d16_hi v140, v124 offset:27272
	ds_write_b16 v140, v125 offset:27408
	ds_write_b16_d16_hi v140, v125 offset:27544
	ds_write_b16 v140, v126 offset:27680
	ds_write_b16_d16_hi v140, v126 offset:27816
	ds_write_b16 v140, v127 offset:27952
	ds_write_b16_d16_hi v140, v127 offset:28088
	s_add_i32 s26, s26, 64
	v_lshl_add_u64 v[132:133], v[132:133], 0, s[4:5]
	v_lshl_add_u64 v[134:135], v[134:135], 0, s[4:5]
	s_waitcnt lgkmcnt(0)
	s_barrier
	global_load_dwordx4 v[120:123], v[134:135], off
	global_load_dwordx4 v[124:127], v[132:133], off
	ds_read_b128 v[148:151], v200 offset:9216
	ds_read_b128 v[152:155], v201 offset:9216
	ds_read_b128 v[156:159], v200 offset:9248
	ds_read_b128 v[160:163], v201 offset:9248
	s_waitcnt lgkmcnt(2)
	v_mfma_f32_32x32x16_bf16 v[96:111], v[148:151], v[112:115], v[48:63]
	v_mfma_f32_32x32x16_bf16 v[80:95], v[152:155], v[112:115], v[48:63]
	s_waitcnt lgkmcnt(0)
	v_mfma_f32_32x32x16_bf16 v[96:111], v[156:159], v[116:119], v[96:111]
	v_mfma_f32_32x32x16_bf16 v[80:95], v[160:163], v[116:119], v[80:95]
	ds_read2_b64 v[164:167], v212 offset0:0 offset1:2
	ds_read2_b64 v[168:171], v213 offset0:32 offset1:34
	ds_read2_b64 v[172:175], v212 offset0:4 offset1:6
	ds_read2_b64 v[180:183], v213 offset0:36 offset1:38
	ds_read2_b64 v[184:187], v212 offset0:8 offset1:10
	ds_read2_b64 v[188:191], v213 offset0:40 offset1:42
	ds_read2_b64 v[192:195], v212 offset0:12 offset1:14
	ds_read2_b64 v[196:199], v213 offset0:44 offset1:46
	s_nop 2
	v_exp_f32_e32 v96, v96
	v_exp_f32_e32 v97, v97
	v_exp_f32_e32 v98, v98
	v_exp_f32_e32 v99, v99
	v_exp_f32_e32 v100, v100
	v_exp_f32_e32 v101, v101
	v_exp_f32_e32 v102, v102
	v_exp_f32_e32 v103, v103
	v_cvt_pk_bf16_f32 v6, v96, v97
	v_cvt_pk_bf16_f32 v7, v98, v99
	v_cvt_pk_bf16_f32 v8, v100, v101
	v_cvt_pk_bf16_f32 v9, v102, v103
	v_exp_f32_e32 v104, v104
	v_exp_f32_e32 v105, v105
	s_waitcnt lgkmcnt(6)
	v_mfma_f32_32x32x16_bf16 v[32:47], v[164:167], v[6:9], v[32:47]
	v_exp_f32_e32 v106, v106
	v_exp_f32_e32 v107, v107
	v_cvt_pk_bf16_f32 v208, v104, v105
	v_mfma_f32_32x32x16_bf16 v[16:31], v[168:171], v[6:9], v[16:31]
	v_exp_f32_e32 v108, v108
	v_exp_f32_e32 v109, v109
	v_cvt_pk_bf16_f32 v209, v106, v107
	v_mfma_f32_32x32x16_bf16 v[64:79], v[204:207], v[6:9], v[64:79]
	v_exp_f32_e32 v110, v110
	v_exp_f32_e32 v111, v111
	v_cvt_pk_bf16_f32 v210, v108, v109
	v_exp_f32_e32 v80, v80
	v_cvt_pk_bf16_f32 v211, v110, v111
	v_exp_f32_e32 v81, v81
	s_waitcnt lgkmcnt(4)
	v_mfma_f32_32x32x16_bf16 v[32:47], v[172:175], v[208:211], v[32:47]
	v_exp_f32_e32 v82, v82
	v_exp_f32_e32 v83, v83
	v_cvt_pk_bf16_f32 v6, v80, v81
	v_mfma_f32_32x32x16_bf16 v[16:31], v[180:183], v[208:211], v[16:31]
	v_exp_f32_e32 v84, v84
	v_exp_f32_e32 v85, v85
	v_cvt_pk_bf16_f32 v7, v82, v83
	v_mfma_f32_32x32x16_bf16 v[64:79], v[204:207], v[208:211], v[64:79]
	v_exp_f32_e32 v86, v86
	v_exp_f32_e32 v87, v87
	v_cvt_pk_bf16_f32 v8, v84, v85
	v_exp_f32_e32 v88, v88
	v_cvt_pk_bf16_f32 v9, v86, v87
	v_exp_f32_e32 v89, v89
	s_waitcnt lgkmcnt(2)
	v_mfma_f32_32x32x16_bf16 v[32:47], v[184:187], v[6:9], v[32:47]
	v_exp_f32_e32 v90, v90
	v_exp_f32_e32 v91, v91
	v_cvt_pk_bf16_f32 v208, v88, v89
	v_mfma_f32_32x32x16_bf16 v[16:31], v[188:191], v[6:9], v[16:31]
	v_exp_f32_e32 v92, v92
	v_exp_f32_e32 v93, v93
	v_cvt_pk_bf16_f32 v209, v90, v91
	v_mfma_f32_32x32x16_bf16 v[64:79], v[204:207], v[6:9], v[64:79]
	v_exp_f32_e32 v94, v94
	v_exp_f32_e32 v95, v95
	v_cvt_pk_bf16_f32 v210, v92, v93
	s_nop 0
	v_cvt_pk_bf16_f32 v211, v94, v95
	s_waitcnt lgkmcnt(0)
	s_nop 0
	v_mfma_f32_32x32x16_bf16 v[32:47], v[192:195], v[208:211], v[32:47]
	v_mfma_f32_32x32x16_bf16 v[16:31], v[196:199], v[208:211], v[16:31]
	v_mfma_f32_32x32x16_bf16 v[64:79], v[204:207], v[208:211], v[64:79]
	s_waitcnt vmcnt(1)
	ds_write_b128 v139, v[120:123]
	s_waitcnt vmcnt(0)
	ds_write_b16 v140, v124 offset:18432
	ds_write_b16_d16_hi v140, v124 offset:18568
	ds_write_b16 v140, v125 offset:18704
	ds_write_b16_d16_hi v140, v125 offset:18840
	ds_write_b16 v140, v126 offset:18976
	ds_write_b16_d16_hi v140, v126 offset:19112
	ds_write_b16 v140, v127 offset:19248
	ds_write_b16_d16_hi v140, v127 offset:19384
	s_add_i32 s26, s26, 64
	v_lshl_add_u64 v[132:133], v[132:133], 0, s[4:5]
	v_lshl_add_u64 v[134:135], v[134:135], 0, s[4:5]
	s_add_i32 s31, s31, 2
	s_cmp_lt_u32 s31, s29
	s_waitcnt lgkmcnt(0)
	s_barrier
	s_cbranch_scc1 .LBB0_741
; #define LAS __attribute__((address_space(3)))
; __device__ __forceinline__ int crow(int r, int hi) { return (r & 3) + 8 * (r >> 2) + 4 * hi; }
; #define ATT_LOAD(t) do { kraw = *(const v4u*)(kp + (size_t)(t) * 64 * ZC); vraw = *(const v4u*)(vp + (size_t)(t) * 64 * ZC); \
;         if (!DIFF && tid < 64) ncv = ncp[(t) * 64 + tid]; } while (0)
; template <bool DIFF>
; __device__ __forceinline__ void attn_unit(CA& A, int l, int b, int hh, int qb, LAS unsigned char* lds, float lam, float lam_init) {
;     ...
;         if (has_next) { ATT_LOAD(DIFF ? t + 1 : t - 1); if (!DIFF) nc_hi = ncp[key0 - 1]; }
;         if (key0 <= qlast) {
;             const LAS unsigned char* Kb = lds + AL_KS + buf * AL_KSZ;
;             const LAS unsigned char* Vb = lds + AL_VT + buf * AL_VSZ;
;             f32x16 p[2];
; #pragma unroll
;             for (int kt = 0; kt < 2; ++kt) {
;                 if (!DIFF) {
;                     const LAS float* nc = (const LAS float*)(lds + AL_NC + buf * 512) + 32 * kt + 4 * hi;
; #pragma unroll
;                     for (int g = 0; g < 4; ++g) { const f32x4 c4 = *(const LAS f32x4*)(nc + 8 * g); p[kt][4 * g] = c4[0]; p[kt][4 * g + 1] = c4[1]; p[kt][4 * g + 2] = c4[2]; p[kt][4 * g + 3] = c4[3]; }
;                 }
; #pragma unroll
;                 for (int s = 0; s < NS; ++s) {
;                     const bf16x8 a = *(const LAS bf16x8*)(Kb + (32 * kt + r32) * 144 + (koff + 16 * s + 8 * hi) * 2);
;                     if (DIFF && s == 0) p[kt] = __builtin_amdgcn_mfma_f32_32x32x16_bf16(a, qf[s], negm, 0, 0, 0);
;                     else p[kt] = __builtin_amdgcn_mfma_f32_32x32x16_bf16(a, qf[s], p[kt], 0, 0, 0);
;                 }
;             }
;             if (!DIFF) {
; #pragma unroll
;                 for (int kt = 0; kt < 2; ++kt)
; #pragma unroll
;                     for (int r = 0; r < 16; ++r) p[kt][r] -= m_ref;
;             }
;             if (key0 + 63 > qfirst) {
; #pragma unroll
;                 for (int kt = 0; kt < 2; ++kt)
; #pragma unroll
;                     for (int r = 0; r < 16; ++r) if (key0 + 32 * kt + crow(r, hi) > qmine) p[kt][r] = -1e30f;
.Lmy_d_final:
	global_load_dwordx4 v[120:123], v[134:135], off
	global_load_dwordx4 v[124:127], v[132:133], off
	ds_read_b128 v[148:151], v200
	ds_read_b128 v[152:155], v201
	ds_read_b128 v[156:159], v200 offset:32
	ds_read_b128 v[160:163], v201 offset:32
	s_waitcnt lgkmcnt(2)
	v_mfma_f32_32x32x16_bf16 v[96:111], v[148:151], v[112:115], v[48:63]
	v_mfma_f32_32x32x16_bf16 v[80:95], v[152:155], v[112:115], v[48:63]
	s_waitcnt lgkmcnt(0)
	v_mfma_f32_32x32x16_bf16 v[96:111], v[156:159], v[116:119], v[96:111]
	v_mfma_f32_32x32x16_bf16 v[80:95], v[160:163], v[116:119], v[80:95]
	ds_read2_b64 v[164:167], v202 offset0:0 offset1:2
	ds_read2_b64 v[168:171], v203 offset0:32 offset1:34
	ds_read2_b64 v[172:175], v202 offset0:4 offset1:6
	ds_read2_b64 v[180:183], v203 offset0:36 offset1:38
	ds_read2_b64 v[184:187], v202 offset0:8 offset1:10
	ds_read2_b64 v[188:191], v203 offset0:40 offset1:42
	ds_read2_b64 v[192:195], v202 offset0:12 offset1:14
	ds_read2_b64 v[196:199], v203 offset0:44 offset1:46
	s_cmp_le_u32 s26, s25
	s_nop 1
	s_cbranch_scc1 .Lmy_df0_pv
	v_add_u32_e32 v1, s26, v131
	v_subrev_u32_e32 v2, 63, v1
	v_cmp_gt_u32_e32 vcc, v2, v138
	s_nop 1
	v_cndmask_b32_e32 v3, v96, v225, vcc
	v_cmp_lt_u32_e32 vcc, v2, v138
	v_subrev_u32_e32 v2, 61, v1
	s_nop 0
	v_cndmask_b32_e32 v96, v3, v96, vcc
	v_cndmask_b32_e32 v97, v225, v97, vcc
	v_cmp_le_u32_e32 vcc, v2, v138
	v_subrev_u32_e32 v2, 60, v1
	s_nop 0
	v_cndmask_b32_e32 v98, v225, v98, vcc
	v_cmp_le_u32_e32 vcc, v2, v138
	v_subrev_u32_e32 v2, 55, v1
	s_nop 0
	v_cndmask_b32_e32 v99, v225, v99, vcc
	v_cmp_le_u32_e32 vcc, v2, v138
	v_subrev_u32_e32 v2, 54, v1
	s_nop 0
	v_cndmask_b32_e32 v100, v225, v100, vcc
	v_cmp_le_u32_e32 vcc, v2, v138
	v_subrev_u32_e32 v2, 53, v1
	s_nop 0
	v_cndmask_b32_e32 v101, v225, v101, vcc
	v_cmp_le_u32_e32 vcc, v2, v138
	v_subrev_u32_e32 v2, 52, v1
	s_nop 0
	v_cndmask_b32_e32 v102, v225, v102, vcc
	v_cmp_le_u32_e32 vcc, v2, v138
	v_subrev_u32_e32 v2, 47, v1
	s_nop 0
	v_cndmask_b32_e32 v103, v225, v103, vcc
	v_cmp_le_u32_e32 vcc, v2, v138
	v_subrev_u32_e32 v2, 46, v1
	s_nop 0
	v_cndmask_b32_e32 v104, v225, v104, vcc
	v_cmp_le_u32_e32 vcc, v2, v138
	v_subrev_u32_e32 v2, 45, v1
	s_nop 0
	v_cndmask_b32_e32 v105, v225, v105, vcc
	v_cmp_le_u32_e32 vcc, v2, v138
	v_subrev_u32_e32 v2, 44, v1
	s_nop 0
	v_cndmask_b32_e32 v106, v225, v106, vcc
	v_cmp_le_u32_e32 vcc, v2, v138
	v_subrev_u32_e32 v2, 39, v1
	s_nop 0
	v_cndmask_b32_e32 v107, v225, v107, vcc
	v_cmp_le_u32_e32 vcc, v2, v138
	v_subrev_u32_e32 v2, 38, v1
	s_nop 0
	v_cndmask_b32_e32 v108, v225, v108, vcc
	v_cmp_le_u32_e32 vcc, v2, v138
	v_subrev_u32_e32 v2, 37, v1
	s_nop 0
	v_cndmask_b32_e32 v109, v225, v109, vcc
	v_cmp_le_u32_e32 vcc, v2, v138
	v_subrev_u32_e32 v2, 36, v1
	s_nop 0
	v_cndmask_b32_e32 v110, v225, v110, vcc
	v_cmp_le_u32_e32 vcc, v2, v138
	v_subrev_u32_e32 v2, 31, v1
	s_nop 0
	v_cndmask_b32_e32 v111, v225, v111, vcc
	v_cmp_le_u32_e32 vcc, v2, v138
	v_subrev_u32_e32 v2, 30, v1
	s_nop 0
	v_cndmask_b32_e32 v80, v225, v80, vcc
	v_cmp_le_u32_e32 vcc, v2, v138
	v_subrev_u32_e32 v2, 29, v1
	s_nop 0
	v_cndmask_b32_e32 v81, v225, v81, vcc
	v_cmp_le_u32_e32 vcc, v2, v138
	v_subrev_u32_e32 v2, 28, v1
	s_nop 0
	v_cndmask_b32_e32 v82, v225, v82, vcc
	v_cmp_le_u32_e32 vcc, v2, v138
	v_subrev_u32_e32 v2, 23, v1
	s_nop 0
	v_cndmask_b32_e32 v83, v225, v83, vcc
	v_cmp_le_u32_e32 vcc, v2, v138
	v_subrev_u32_e32 v2, 22, v1
	s_nop 0
	v_cndmask_b32_e32 v84, v225, v84, vcc
	v_cmp_le_u32_e32 vcc, v2, v138
	v_subrev_u32_e32 v2, 21, v1
	s_nop 0
	v_cndmask_b32_e32 v85, v225, v85, vcc
	v_cmp_le_u32_e32 vcc, v2, v138
	v_subrev_u32_e32 v2, 20, v1
	s_nop 0
	v_cndmask_b32_e32 v86, v225, v86, vcc
	v_cmp_le_u32_e32 vcc, v2, v138
	v_add_u32_e32 v2, -15, v1
	s_nop 0
	v_cndmask_b32_e32 v87, v225, v87, vcc
	v_cmp_le_u32_e32 vcc, v2, v138
	v_add_u32_e32 v2, -14, v1
	s_nop 0
	v_cndmask_b32_e32 v88, v225, v88, vcc
	v_cmp_le_u32_e32 vcc, v2, v138
	v_add_u32_e32 v2, -13, v1
	s_nop 0
	v_cndmask_b32_e32 v89, v225, v89, vcc
	v_cmp_le_u32_e32 vcc, v2, v138
	v_add_u32_e32 v2, -12, v1
	s_nop 0
	v_cndmask_b32_e32 v90, v225, v90, vcc
	v_cmp_le_u32_e32 vcc, v2, v138
	v_add_u32_e32 v2, -7, v1
	s_nop 0
	v_cndmask_b32_e32 v91, v225, v91, vcc
	v_cmp_le_u32_e32 vcc, v2, v138
	v_add_u32_e32 v2, -6, v1
	s_nop 0
	v_cndmask_b32_e32 v92, v225, v92, vcc
	v_cmp_le_u32_e32 vcc, v2, v138
	v_add_u32_e32 v2, -5, v1
	v_add_u32_e32 v1, -4, v1
	v_cndmask_b32_e32 v93, v225, v93, vcc
	v_cmp_le_u32_e32 vcc, v2, v138
	s_nop 1
	v_cndmask_b32_e32 v94, v225, v94, vcc
	v_cmp_le_u32_e32 vcc, v1, v138
	s_nop 1
	v_cndmask_b32_e32 v95, v225, v95, vcc
; template <bool DIFF>
; __device__ __forceinline__ void attn_unit(CA& A, int l, int b, int hh, int qb, LAS unsigned char* lds, float lam, float lam_init) {
;     ...
;         if (key0 <= qlast) {
;             const LAS unsigned char* Kb = lds + AL_KS + buf * AL_KSZ;
;             const LAS unsigned char* Vb = lds + AL_VT + buf * AL_VSZ;
;             f32x16 p[2];
; #pragma unroll
;             for (int kt = 0; kt < 2; ++kt) {
;                 if (!DIFF) {
;                     const LAS float* nc = (const LAS float*)(lds + AL_NC + buf * 512) + 32 * kt + 4 * hi;
; #pragma unroll
;                     for (int g = 0; g < 4; ++g) { const f32x4 c4 = *(const LAS f32x4*)(nc + 8 * g); p[kt][4 * g] = c4[0]; p[kt][4 * g + 1] = c4[1]; p[kt][4 * g + 2] = c4[2]; p[kt][4 * g + 3] = c4[3]; }
;     ...
; #pragma unroll
;             for (int kt = 0; kt < 2; ++kt)
; #pragma unroll
;                 for (int r = 0; r < 16; ++r) p[kt][r] = __builtin_amdgcn_exp2f(p[kt][r]);
;             bf16x8 pb[2][2];
; #pragma unroll
;             for (int kt = 0; kt < 2; ++kt)
; #pragma unroll
;                 for (int i = 0; i < 2; ++i) { v4u w;
; #pragma unroll
;                     for (int j = 0; j < 4; ++j) w[j] = pk2(p[kt][8 * i + 2 * j], p[kt][8 * i + 2 * j + 1]);
;                     pb[kt][i] = __builtin_bit_cast(bf16x8, w); }
; #pragma unroll
;             for (int kt = 0; kt < 2; ++kt)
; #pragma unroll
;                 for (int i = 0; i < 2; ++i) {
; #pragma unroll
;                     for (int dt = 0; dt < 2; ++dt) {
;                         const LAS unsigned char* vq = Vb + (32 * dt + r32) * 136 + (32 * kt + 16 * i + 4 * hi) * 2;
;                         const s16x4 lo = *(const LAS s16x4*)vq, h4 = *(const LAS s16x4*)(vq + 16);
;                         const bf16x8 a = {lo[0], lo[1], lo[2], lo[3], h4[0], h4[1], h4[2], h4[3]};
;                         o[dt] = __builtin_amdgcn_mfma_f32_32x32x16_bf16(a, pb[kt][i], o[dt], 0, 0, 0);
;                     }
;                     ol = __builtin_amdgcn_mfma_f32_32x32x16_bf16(ones, pb[kt][i], ol, 0, 0, 0);
;                 }
;         }
;         if (has_next) ATT_WRITE(buf ^ 1);
;         if (!DIFF) {
;             const int vote = (!first && !__any(nc_hi + qkb - m_ref + 2.0f * qkb >= -48.0f)) ? 1 : 0;
;             if (lane == 0) votes[(tt & 1) * 8 + wid] = vote;
;         }
;         __syncthreads();
;         if (!has_next) break;
.Lmy_df0_pv:
	v_exp_f32_e32 v96, v96
	v_exp_f32_e32 v97, v97
	v_exp_f32_e32 v98, v98
	v_exp_f32_e32 v99, v99
	v_exp_f32_e32 v100, v100
	v_exp_f32_e32 v101, v101
	v_exp_f32_e32 v102, v102
	v_exp_f32_e32 v103, v103
	v_cvt_pk_bf16_f32 v6, v96, v97
	v_cvt_pk_bf16_f32 v7, v98, v99
	v_cvt_pk_bf16_f32 v8, v100, v101
	v_cvt_pk_bf16_f32 v9, v102, v103
	v_exp_f32_e32 v104, v104
	v_exp_f32_e32 v105, v105
	s_waitcnt lgkmcnt(6)
	v_mfma_f32_32x32x16_bf16 v[32:47], v[164:167], v[6:9], v[32:47]
	v_exp_f32_e32 v106, v106
	v_exp_f32_e32 v107, v107
	v_cvt_pk_bf16_f32 v208, v104, v105
	v_mfma_f32_32x32x16_bf16 v[16:31], v[168:171], v[6:9], v[16:31]
	v_exp_f32_e32 v108, v108
	v_exp_f32_e32 v109, v109
	v_cvt_pk_bf16_f32 v209, v106, v107
	v_mfma_f32_32x32x16_bf16 v[64:79], v[204:207], v[6:9], v[64:79]
	v_exp_f32_e32 v110, v110
	v_exp_f32_e32 v111, v111
	v_cvt_pk_bf16_f32 v210, v108, v109
	v_exp_f32_e32 v80, v80
	v_cvt_pk_bf16_f32 v211, v110, v111
	v_exp_f32_e32 v81, v81
	s_waitcnt lgkmcnt(4)
	v_mfma_f32_32x32x16_bf16 v[32:47], v[172:175], v[208:211], v[32:47]
	v_exp_f32_e32 v82, v82
	v_exp_f32_e32 v83, v83
	v_cvt_pk_bf16_f32 v6, v80, v81
	v_mfma_f32_32x32x16_bf16 v[16:31], v[180:183], v[208:211], v[16:31]
	v_exp_f32_e32 v84, v84
	v_exp_f32_e32 v85, v85
	v_cvt_pk_bf16_f32 v7, v82, v83
	v_mfma_f32_32x32x16_bf16 v[64:79], v[204:207], v[208:211], v[64:79]
	v_exp_f32_e32 v86, v86
	v_exp_f32_e32 v87, v87
	v_cvt_pk_bf16_f32 v8, v84, v85
	v_exp_f32_e32 v88, v88
	v_cvt_pk_bf16_f32 v9, v86, v87
	v_exp_f32_e32 v89, v89
	s_waitcnt lgkmcnt(2)
	v_mfma_f32_32x32x16_bf16 v[32:47], v[184:187], v[6:9], v[32:47]
	v_exp_f32_e32 v90, v90
	v_exp_f32_e32 v91, v91
	v_cvt_pk_bf16_f32 v208, v88, v89
	v_mfma_f32_32x32x16_bf16 v[16:31], v[188:191], v[6:9], v[16:31]
	v_exp_f32_e32 v92, v92
	v_exp_f32_e32 v93, v93
	v_cvt_pk_bf16_f32 v209, v90, v91
	v_mfma_f32_32x32x16_bf16 v[64:79], v[204:207], v[6:9], v[64:79]
	v_exp_f32_e32 v94, v94
	v_exp_f32_e32 v95, v95
	v_cvt_pk_bf16_f32 v210, v92, v93
	s_nop 0
	v_cvt_pk_bf16_f32 v211, v94, v95
	s_waitcnt lgkmcnt(0)
	s_nop 0
	v_mfma_f32_32x32x16_bf16 v[32:47], v[192:195], v[208:211], v[32:47]
	v_mfma_f32_32x32x16_bf16 v[16:31], v[196:199], v[208:211], v[16:31]
	v_mfma_f32_32x32x16_bf16 v[64:79], v[204:207], v[208:211], v[64:79]
	s_waitcnt vmcnt(1)
	ds_write_b128 v139, v[120:123] offset:9216
	s_waitcnt vmcnt(0)
	ds_write_b16 v140, v124 offset:27136
	ds_write_b16_d16_hi v140, v124 offset:27272
	ds_write_b16 v140, v125 offset:27408
	ds_write_b16_d16_hi v140, v125 offset:27544
	ds_write_b16 v140, v126 offset:27680
	ds_write_b16_d16_hi v140, v126 offset:27816
	ds_write_b16 v140, v127 offset:27952
	ds_write_b16_d16_hi v140, v127 offset:28088
	s_add_i32 s26, s26, 64
	s_waitcnt lgkmcnt(0)
	s_barrier
	s_sub_i32 s30, s26, 63
	s_cmp_gt_u32 s30, s28
	s_cbranch_scc1 .Lmy_df_skip
	ds_read_b128 v[148:151], v200 offset:9216
	ds_read_b128 v[152:155], v201 offset:9216
	ds_read_b128 v[156:159], v200 offset:9248
	ds_read_b128 v[160:163], v201 offset:9248
	s_waitcnt lgkmcnt(2)
	v_mfma_f32_32x32x16_bf16 v[96:111], v[148:151], v[112:115], v[48:63]
	v_mfma_f32_32x32x16_bf16 v[80:95], v[152:155], v[112:115], v[48:63]
	s_waitcnt lgkmcnt(0)
	v_mfma_f32_32x32x16_bf16 v[96:111], v[156:159], v[116:119], v[96:111]
	v_mfma_f32_32x32x16_bf16 v[80:95], v[160:163], v[116:119], v[80:95]
	ds_read2_b64 v[164:167], v212 offset0:0 offset1:2
	ds_read2_b64 v[168:171], v213 offset0:32 offset1:34
	ds_read2_b64 v[172:175], v212 offset0:4 offset1:6
	ds_read2_b64 v[180:183], v213 offset0:36 offset1:38
	ds_read2_b64 v[184:187], v212 offset0:8 offset1:10
	ds_read2_b64 v[188:191], v213 offset0:40 offset1:42
	ds_read2_b64 v[192:195], v212 offset0:12 offset1:14
	ds_read2_b64 v[196:199], v213 offset0:44 offset1:46
	s_cmp_le_u32 s26, s25
	s_nop 1
	s_cbranch_scc1 .Lmy_df1_pv
; __device__ __forceinline__ int crow(int r, int hi) { return (r & 3) + 8 * (r >> 2) + 4 * hi; }
; template <bool DIFF>
; __device__ __forceinline__ void attn_unit(CA& A, int l, int b, int hh, int qb, LAS unsigned char* lds, float lam, float lam_init) {
;     ...
;             if (key0 + 63 > qfirst) {
; #pragma unroll
;                 for (int kt = 0; kt < 2; ++kt)
; #pragma unroll
;                     for (int r = 0; r < 16; ++r) if (key0 + 32 * kt + crow(r, hi) > qmine) p[kt][r] = -1e30f;
;             }
	v_add_u32_e32 v1, s26, v131
	v_subrev_u32_e32 v2, 63, v1
	v_cmp_gt_u32_e32 vcc, v2, v138
	s_nop 1
	v_cndmask_b32_e32 v3, v96, v225, vcc
	v_cmp_lt_u32_e32 vcc, v2, v138
	v_subrev_u32_e32 v2, 61, v1
	s_nop 0
	v_cndmask_b32_e32 v96, v3, v96, vcc
	v_cndmask_b32_e32 v97, v225, v97, vcc
	v_cmp_le_u32_e32 vcc, v2, v138
	v_subrev_u32_e32 v2, 60, v1
	s_nop 0
	v_cndmask_b32_e32 v98, v225, v98, vcc
	v_cmp_le_u32_e32 vcc, v2, v138
	v_subrev_u32_e32 v2, 55, v1
	s_nop 0
	v_cndmask_b32_e32 v99, v225, v99, vcc
	v_cmp_le_u32_e32 vcc, v2, v138
	v_subrev_u32_e32 v2, 54, v1
	s_nop 0
	v_cndmask_b32_e32 v100, v225, v100, vcc
	v_cmp_le_u32_e32 vcc, v2, v138
	v_subrev_u32_e32 v2, 53, v1
	s_nop 0
	v_cndmask_b32_e32 v101, v225, v101, vcc
	v_cmp_le_u32_e32 vcc, v2, v138
	v_subrev_u32_e32 v2, 52, v1
	s_nop 0
	v_cndmask_b32_e32 v102, v225, v102, vcc
	v_cmp_le_u32_e32 vcc, v2, v138
	v_subrev_u32_e32 v2, 47, v1
	s_nop 0
	v_cndmask_b32_e32 v103, v225, v103, vcc
	v_cmp_le_u32_e32 vcc, v2, v138
	v_subrev_u32_e32 v2, 46, v1
	s_nop 0
	v_cndmask_b32_e32 v104, v225, v104, vcc
	v_cmp_le_u32_e32 vcc, v2, v138
	v_subrev_u32_e32 v2, 45, v1
	s_nop 0
	v_cndmask_b32_e32 v105, v225, v105, vcc
	v_cmp_le_u32_e32 vcc, v2, v138
	v_subrev_u32_e32 v2, 44, v1
	s_nop 0
	v_cndmask_b32_e32 v106, v225, v106, vcc
	v_cmp_le_u32_e32 vcc, v2, v138
	v_subrev_u32_e32 v2, 39, v1
	s_nop 0
	v_cndmask_b32_e32 v107, v225, v107, vcc
	v_cmp_le_u32_e32 vcc, v2, v138
	v_subrev_u32_e32 v2, 38, v1
	s_nop 0
	v_cndmask_b32_e32 v108, v225, v108, vcc
	v_cmp_le_u32_e32 vcc, v2, v138
	v_subrev_u32_e32 v2, 37, v1
	s_nop 0
	v_cndmask_b32_e32 v109, v225, v109, vcc
	v_cmp_le_u32_e32 vcc, v2, v138
	v_subrev_u32_e32 v2, 36, v1
	s_nop 0
	v_cndmask_b32_e32 v110, v225, v110, vcc
	v_cmp_le_u32_e32 vcc, v2, v138
	v_subrev_u32_e32 v2, 31, v1
	s_nop 0
	v_cndmask_b32_e32 v111, v225, v111, vcc
	v_cmp_le_u32_e32 vcc, v2, v138
	v_subrev_u32_e32 v2, 30, v1
	s_nop 0
	v_cndmask_b32_e32 v80, v225, v80, vcc
	v_cmp_le_u32_e32 vcc, v2, v138
	v_subrev_u32_e32 v2, 29, v1
	s_nop 0
	v_cndmask_b32_e32 v81, v225, v81, vcc
	v_cmp_le_u32_e32 vcc, v2, v138
	v_subrev_u32_e32 v2, 28, v1
	s_nop 0
	v_cndmask_b32_e32 v82, v225, v82, vcc
	v_cmp_le_u32_e32 vcc, v2, v138
	v_subrev_u32_e32 v2, 23, v1
	s_nop 0
	v_cndmask_b32_e32 v83, v225, v83, vcc
	v_cmp_le_u32_e32 vcc, v2, v138
	v_subrev_u32_e32 v2, 22, v1
	s_nop 0
	v_cndmask_b32_e32 v84, v225, v84, vcc
	v_cmp_le_u32_e32 vcc, v2, v138
	v_subrev_u32_e32 v2, 21, v1
	s_nop 0
	v_cndmask_b32_e32 v85, v225, v85, vcc
	v_cmp_le_u32_e32 vcc, v2, v138
	v_subrev_u32_e32 v2, 20, v1
	s_nop 0
	v_cndmask_b32_e32 v86, v225, v86, vcc
	v_cmp_le_u32_e32 vcc, v2, v138
	v_add_u32_e32 v2, -15, v1
	s_nop 0
	v_cndmask_b32_e32 v87, v225, v87, vcc
	v_cmp_le_u32_e32 vcc, v2, v138
	v_add_u32_e32 v2, -14, v1
	s_nop 0
	v_cndmask_b32_e32 v88, v225, v88, vcc
	v_cmp_le_u32_e32 vcc, v2, v138
	v_add_u32_e32 v2, -13, v1
	s_nop 0
	v_cndmask_b32_e32 v89, v225, v89, vcc
	v_cmp_le_u32_e32 vcc, v2, v138
	v_add_u32_e32 v2, -12, v1
	s_nop 0
	v_cndmask_b32_e32 v90, v225, v90, vcc
	v_cmp_le_u32_e32 vcc, v2, v138
	v_add_u32_e32 v2, -7, v1
	s_nop 0
	v_cndmask_b32_e32 v91, v225, v91, vcc
	v_cmp_le_u32_e32 vcc, v2, v138
	v_add_u32_e32 v2, -6, v1
	s_nop 0
	v_cndmask_b32_e32 v92, v225, v92, vcc
	v_cmp_le_u32_e32 vcc, v2, v138
	v_add_u32_e32 v2, -5, v1
	v_add_u32_e32 v1, -4, v1
	v_cndmask_b32_e32 v93, v225, v93, vcc
	v_cmp_le_u32_e32 vcc, v2, v138
	s_nop 1
	v_cndmask_b32_e32 v94, v225, v94, vcc
	v_cmp_le_u32_e32 vcc, v1, v138
	s_nop 1
	v_cndmask_b32_e32 v95, v225, v95, vcc

; template <bool DIFF>
; __device__ __forceinline__ void attn_unit(CA& A, int l, int b, int hh, int qb, LAS unsigned char* lds, float lam, float lam_init) {
;     ...
;         if (has_next) ATT_WRITE(buf ^ 1);
;         if (!DIFF) {
;             const int vote = (!first && !__any(nc_hi + qkb - m_ref + 2.0f * qkb >= -48.0f)) ? 1 : 0;
;             if (lane == 0) votes[(tt & 1) * 8 + wid] = vote;
;         }
;         __syncthreads();
;         if (!has_next) break;
.Lmy_df_skip:
	s_waitcnt lgkmcnt(0)
	s_barrier
